# grid barrier between the PLE projection phase and layer 0's in-projection removed (the in-projection reads nothing the PLE phase writes)
# speedup vs baseline: 1.0046x; 1.0046x over previous
; __device__ __forceinline__ unsigned xb_add(unsigned* p, unsigned v) { return __hip_atomic_fetch_add(p, v, __ATOMIC_RELAXED, __HIP_MEMORY_SCOPE_AGENT); }
; __device__ __forceinline__ int xb_lane() { int ln; asm volatile("v_mbcnt_lo_u32_b32 %0, -1, 0\n\tv_mbcnt_hi_u32_b32 %0, -1, %0" : "=v"(ln)); return ln; }
; #define SEAM(k) do { if (IN(k) && IN((k) + 1)) xcd_barrier(bar); } while (0)
; __device__ __forceinline__ void xcd_barrier(const XcdBarrier& b) {
;     asm volatile("s_waitcnt vmcnt(0)" ::: "memory");
;     __syncthreads();
;     if (b.w0 && xb_lane() == 0) {
;         unsigned* bar = b.bar; asm volatile("" : "+s"(bar));
;         __builtin_amdgcn_s_waitcnt(0);
;         unsigned nloc = b.st[0], nx = b.st[1];
;         if (nloc == 0u) { xcd_barrier_complete(bar, b.x, nloc, nx); b.st[0] = nloc; b.st[1] = nx; }
;         const unsigned old = xb_add(&bar[XB_XSUB(b.x)], 1u);
; __global__ void __launch_bounds__(512, 2) fwd_kernel(Args a) {
;     ...
;     } SEAM(1);
.LBB0_288:
	v_readlane_b32 s0, v253, 9
	v_readlane_b32 s1, v253, 10
	s_cmp_lt_i32 s1, 3
	s_mov_b64 s[0:1], -1
	v_readlane_b32 s2, v253, 11
	v_readlane_b32 s3, v253, 12
	v_writelane_b32 v253, s0, 19
	s_cselect_b64 s[2:3], -1, 0
	s_nop 0
	v_writelane_b32 v253, s1, 20
	s_xor_b64 s[0:1], s[4:5], -1
	s_or_b64 s[0:1], s[0:1], s[2:3]
	s_and_b64 vcc, exec, s[0:1]
	s_branch .LBB0_336
	s_waitcnt vmcnt(0)
	v_readlane_b32 s0, v253, 15
	v_readlane_b32 s1, v253, 16
	s_and_b64 vcc, exec, s[0:1]
	s_waitcnt vmcnt(0)
	s_barrier
	s_cbranch_vccnz .LBB0_335
	v_mbcnt_lo_u32_b32 v0, -1, 0
	v_mbcnt_hi_u32_b32 v0, -1, v0
	s_nop 0
	v_cmp_eq_u32_e32 vcc, 0, v0
	s_and_saveexec_b64 s[0:1], vcc
	s_cbranch_execz .LBB0_334
	v_readlane_b32 s8, v253, 7
	v_readlane_b32 s2, v253, 13
	v_readlane_b32 s9, v253, 8
	s_waitcnt vmcnt(0) expcnt(0) lgkmcnt(0)
	v_mov_b32_e32 v0, s2
	ds_read_b32 v2, v0
	ds_read_b32 v0, v0 offset:4
	s_waitcnt lgkmcnt(1)
	v_cmp_ne_u32_e32 vcc, 0, v2
	s_cbranch_vccnz .LBB0_305
	v_readlane_b32 s4, v253, 1
	v_readlane_b32 s5, v253, 2
	s_load_dwordx2 s[2:3], s[4:5], 0x4
	s_add_u32 s4, s8, 0x1000
	s_addc_u32 s5, s9, 0
	s_add_u32 s6, s8, 0x1100
	s_addc_u32 s7, s9, 0
	v_readlane_b32 s10, v253, 3
	v_readlane_b32 s11, v253, 4
	s_waitcnt lgkmcnt(0)
	s_mul_i32 s22, s2, s10
	s_add_u32 s10, s8, 0x1200
	s_addc_u32 s11, s9, 0
	s_add_u32 s12, s8, 0x1300
	s_addc_u32 s13, s9, 0
	s_mul_i32 s22, s22, s3
	s_mov_b32 s23, 1
	s_mov_b64 s[2:3], 0
	v_mov_b64_e32 v[0:1], s[8:9]
	v_mov_b64_e32 v[2:3], s[4:5]
	v_mov_b64_e32 v[4:5], s[6:7]
	v_mov_b64_e32 v[6:7], s[10:11]
	v_mov_b64_e32 v[8:9], s[12:13]
	s_branch .LBB0_295
